# layer 1: 448 (was 384) of the 512 mixer-A units dealt after the M2 queue, now that attention units are shorter; on comb15
# baseline (speedup 1.0000x reference)
;     template <class T> __device__ __forceinline__ T* w(size_t off) const { return (T*)(pp->ws + off); }
; __device__ __forceinline__ float wave_sum(float v) { v = row16_sum(v); return (rlf(v, 0) + rlf(v, 16)) + (rlf(v, 32) + rlf(v, 48)); }
; __device__ __forceinline__ void mixA_unit(const Ctx& c, int l, int a) {
;     ...
;     const bf16* VA = c.w<bf16>(WS_VA) + (size_t)r0 * 1024; const bf16* UA = c.w<bf16>(WS_UA) + (size_t)r0 * 1024; const bf16* ZA = c.w<bf16>(WS_ZA) + (size_t)r0 * 1024;
;     const int lane = c.lane, wave = c.wave, m = lane & 15, quad = lane >> 4;
; #pragma unroll
;     for (int half = 0; half < 2; ++half) {
;         u32x4 raw[8][2];
; #pragma unroll
;         for (int i = 0; i < 8; ++i) { const bf16* row = VA + (size_t)(wave * 16 + half * 8 + i) * 1024; raw[i][0] = *(const u32x4*)(row + lane * 8); raw[i][1] = *(const u32x4*)(row + 512 + lane * 8); }
; #pragma unroll
;         for (int i = 0; i < 8; ++i) {
;             float x[8], y[8]; unpack8(raw[i][0], x); unpack8(raw[i][1], y);
;             float sm = 0.f, sq = 0.f;
; #pragma unroll
;             for (int e = 0; e < 8; ++e) { sm += x[e] + y[e]; sq += x[e] * x[e] + y[e] * y[e]; }
;             sm = wave_sum(sm); sq = wave_sum(sq);
;             const float mu = sm * (1.0f / 1024.0f), var = fmaxf(sq * (1.0f / 1024.0f) - mu * mu, 0.f);
;             if (lane == 0) { st_mean[wave * 16 + half * 8 + i] = mu; st_rstd[wave * 16 + half * 8 + i] = rsqrtf(var + 1e-6f); }
;         }
; __device__ __forceinline__ void m1_dispatch(const Ctx& c, int l, int u) {
;     if (u < M1_NX) { if (u < 8) mixA_sample(c, l, u); else mixB_prep(c, l, u - 8); return; }
;     u -= M1_NX;
;     if (u < M1_NI) { dsa_index_unit(c, l, u & 3, 63 - (u >> 2)); return; }
;     u -= M1_NI;
;     if (u < M1_NS) { ssc_unit(c, l, u >> 4, u & 15); return; }
;     u -= M1_NS;
;     if (u < M1_ND) {
;         dprep_unit(c, l, u >> 8, (u >> 3) & 31, u & 7); __syncthreads(); dprep_unit(c, l, u >> 8, (u >> 3) & 31, (u & 7) + 8);
;     }
;     else mixA_unit(c, l, u - M1_ND);
; }
; __device__ __forceinline__ void phase_M1(Ctx& c, int l, int q, const XcdBarrier& bar) {
;     for (;;) {
;         const int u = next_unit(c, q);
;         if (u >= M1_TOTAL) break;
;         m1_dispatch(c, l, u);
.LBB0_2562:
	s_or_b64 exec, exec, s[0:1]
	s_waitcnt lgkmcnt(0)
	s_barrier
	ds_read_b32 v0, v136
	s_mov_b64 s[0:1], -1
	s_waitcnt lgkmcnt(0)
	v_readfirstlane_b32 s18, v0
	v_readlane_b32 s44, v255, 62
	s_nop 3
	s_mul_i32 s45, s44, 0x5d0
	s_add_i32 s18, s18, s45
	s_mul_i32 s45, s44, 0x1c0
	s_addk_i32 s45, 0x5cf
	s_cmp_gt_i32 s18, s45
	s_cbranch_scc1 .LBB0_2557
	s_cmp_gt_i32 s18, 15
	s_cbranch_scc0 .LBB0_2647
	s_cmpk_gt_u32 s18, 0x10f
	s_cbranch_scc0 .LBB0_2626
	s_cmpk_gt_u32 s18, 0x18f
	s_cbranch_scc0 .LBB0_2613
	s_cmpk_gt_u32 s18, 0x58f
	s_cbranch_scc0 .LBB0_2609
	s_lshl_b32 s0, s18, 4
	s_addk_i32 s0, 0x700
	s_and_b32 s10, s0, 0x1f80
	v_readlane_b32 s0, v251, 63
	v_mov_b32_e32 v60, v17
	v_lshlrev_b32_e32 v58, 3, v66
	v_mov_b32_e32 v63, s0
	v_readlane_b32 s0, v252, 0
	v_ashrrev_i32_e32 v59, 31, v58
	v_lshlrev_b64 v[68:69], 1, v[58:59]
	v_mov_b32_e32 v61, s0
	v_readlane_b32 s0, v252, 1
	v_readlane_b32 s2, v251, 40
	v_cmp_eq_u32_e32 vcc, 0, v66
	v_mov_b32_e32 v65, s0
	s_load_dwordx2 s[4:5], s[90:91], 0xc0
	s_lshl_b32 s0, s10, 11
	v_readlane_b32 s3, v251, 41
	s_waitcnt lgkmcnt(0)
	s_add_u32 s0, s4, s0
	s_addc_u32 s1, s5, 0
	s_add_u32 s6, s0, 0x24700000
	s_addc_u32 s7, s1, 0
	v_readlane_b32 s0, v250, 44
	v_readlane_b32 s1, v250, 45
	s_add_u32 s0, s6, s0
	s_addc_u32 s1, s7, s1
	v_lshl_add_u64 v[0:1], s[0:1], 0, v[68:69]
	global_load_dwordx4 v[70:73], v[0:1], off
	global_load_dwordx4 v[74:77], v[0:1], off offset:1024
	v_readlane_b32 s0, v250, 46
	v_readlane_b32 s1, v250, 47
	s_add_u32 s0, s6, s0
	s_addc_u32 s1, s7, s1
	v_lshl_add_u64 v[0:1], s[0:1], 0, v[68:69]
	v_readlane_b32 s0, v250, 48
	v_readlane_b32 s1, v250, 49
	s_add_u32 s0, s6, s0
	s_addc_u32 s1, s7, s1
	global_load_dwordx4 v[54:57], v[0:1], off
	global_load_dwordx4 v[50:53], v[0:1], off offset:1024
	v_lshl_add_u64 v[0:1], s[0:1], 0, v[68:69]
	v_readlane_b32 s0, v250, 50
	v_readlane_b32 s1, v250, 51
	s_add_u32 s0, s6, s0
	s_addc_u32 s1, s7, s1
	global_load_dwordx4 v[46:49], v[0:1], off
	global_load_dwordx4 v[42:45], v[0:1], off offset:1024
	v_lshl_add_u64 v[0:1], s[0:1], 0, v[68:69]
	v_readlane_b32 s0, v250, 52
	v_readlane_b32 s1, v250, 53
	s_add_u32 s0, s6, s0
	s_addc_u32 s1, s7, s1
	global_load_dwordx4 v[38:41], v[0:1], off
	global_load_dwordx4 v[34:37], v[0:1], off offset:1024
	v_lshl_add_u64 v[0:1], s[0:1], 0, v[68:69]
	v_readlane_b32 s0, v250, 54
	v_readlane_b32 s1, v250, 55
	s_add_u32 s0, s6, s0
	s_addc_u32 s1, s7, s1
	global_load_dwordx4 v[30:33], v[0:1], off
	global_load_dwordx4 v[26:29], v[0:1], off offset:1024
	v_lshl_add_u64 v[0:1], s[0:1], 0, v[68:69]
	v_readlane_b32 s0, v250, 56
	v_readlane_b32 s1, v250, 57
	s_add_u32 s0, s6, s0
	s_addc_u32 s1, s7, s1
	global_load_dwordx4 v[22:25], v[0:1], off
	global_load_dwordx4 v[18:21], v[0:1], off offset:1024
	v_lshl_add_u64 v[0:1], s[0:1], 0, v[68:69]
	v_readlane_b32 s0, v250, 58
	v_readlane_b32 s1, v250, 59
	s_add_u32 s0, s6, s0
	s_addc_u32 s1, s7, s1
	global_load_dwordx4 v[12:15], v[0:1], off
	global_load_dwordx4 v[8:11], v[0:1], off offset:1024
	v_lshl_add_u64 v[0:1], s[0:1], 0, v[68:69]
	global_load_dwordx4 v[4:7], v[0:1], off
	s_nop 0
	global_load_dwordx4 v[0:3], v[0:1], off offset:1024
	s_waitcnt vmcnt(15)
	v_lshlrev_b32_e32 v16, 16, v70
	s_waitcnt vmcnt(14)
	v_lshlrev_b32_e32 v79, 16, v74
	v_and_b32_e32 v59, 0xffff0000, v70
	v_and_b32_e32 v74, 0xffff0000, v74
	v_add_f32_e32 v83, v16, v79
	v_mul_f32_e32 v79, v79, v79
	v_fmac_f32_e32 v79, v16, v16
	v_add_f32_e32 v16, v59, v74
	v_mul_f32_e32 v74, v74, v74
	v_lshlrev_b32_e32 v67, 16, v71
	v_lshlrev_b32_e32 v80, 16, v75
	v_add_f32_e32 v83, 0, v83
	v_fmac_f32_e32 v74, v59, v59
	v_add_f32_e32 v16, v16, v83
	v_add_f32_e32 v59, v79, v74
	v_add_f32_e32 v74, v67, v80
	v_and_b32_e32 v70, 0xffff0000, v71
	v_and_b32_e32 v75, 0xffff0000, v75
	v_add_f32_e32 v16, v74, v16
	v_mul_f32_e32 v74, v80, v80
	v_fmac_f32_e32 v74, v67, v67
	v_add_f32_e32 v67, v70, v75
	v_add_f32_e32 v16, v67, v16
	v_mul_f32_e32 v67, v75, v75
	v_lshlrev_b32_e32 v71, 16, v72
	v_lshlrev_b32_e32 v81, 16, v76
	v_add_f32_e32 v59, v74, v59
	v_fmac_f32_e32 v67, v70, v70
	v_add_f32_e32 v59, v67, v59
	v_add_f32_e32 v67, v71, v81
	v_add_f32_e32 v16, v67, v16
	v_mul_f32_e32 v67, v81, v81
	v_and_b32_e32 v72, 0xffff0000, v72
	v_and_b32_e32 v76, 0xffff0000, v76
	v_fmac_f32_e32 v67, v71, v71
	v_add_f32_e32 v59, v67, v59
	v_add_f32_e32 v67, v72, v76
	v_add_f32_e32 v16, v67, v16
	v_mul_f32_e32 v67, v76, v76
	v_lshlrev_b32_e32 v78, 16, v73
	v_lshlrev_b32_e32 v82, 16, v77
	v_fmac_f32_e32 v67, v72, v72
	v_add_f32_e32 v59, v67, v59
	v_add_f32_e32 v67, v78, v82
	v_add_f32_e32 v16, v67, v16
	v_mul_f32_e32 v67, v82, v82
	v_and_b32_e32 v73, 0xffff0000, v73
	v_and_b32_e32 v77, 0xffff0000, v77
	v_fmac_f32_e32 v67, v78, v78
	v_add_f32_e32 v59, v67, v59
	v_add_f32_e32 v67, v73, v77
	v_add_f32_e32 v16, v67, v16
	v_mul_f32_e32 v67, v77, v77
	v_fmac_f32_e32 v67, v73, v73
	v_add_f32_dpp v16, v16, v16 quad_perm:[1,0,3,2] row_mask:0xf bank_mask:0xf bound_ctrl:1
	v_add_f32_e32 v59, v67, v59
	s_nop 0
	v_add_f32_dpp v16, v16, v16 quad_perm:[2,3,0,1] row_mask:0xf bank_mask:0xf bound_ctrl:1
	s_nop 1
	v_add_f32_dpp v16, v16, v16 row_half_mirror row_mask:0xf bank_mask:0xf bound_ctrl:1
	s_nop 1
	v_add_f32_dpp v16, v16, v16 row_mirror row_mask:0xf bank_mask:0xf bound_ctrl:1
	s_nop 0
	v_readlane_b32 s9, v16, 0
	v_readlane_b32 s12, v16, 16
	v_readlane_b32 s1, v16, 32
	v_readlane_b32 s11, v16, 48
	v_add_f32_dpp v16, v59, v59 quad_perm:[1,0,3,2] row_mask:0xf bank_mask:0xf bound_ctrl:1
	s_nop 1
	v_add_f32_dpp v16, v16, v16 quad_perm:[2,3,0,1] row_mask:0xf bank_mask:0xf bound_ctrl:1
	s_nop 1
	v_add_f32_dpp v16, v16, v16 row_half_mirror row_mask:0xf bank_mask:0xf bound_ctrl:1
	s_nop 1
	v_add_f32_dpp v16, v16, v16 row_mirror row_mask:0xf bank_mask:0xf bound_ctrl:1
	s_nop 0
	v_readlane_b32 s8, v16, 0
	v_readlane_b32 s14, v16, 16
	v_readlane_b32 s0, v16, 32
	v_readlane_b32 s13, v16, 48
	v_lshl_add_u32 v16, s2, 2, v65
	s_and_saveexec_b64 s[2:3], vcc
	s_cbranch_execz .LBB0_2569
	v_mov_b32_e32 v70, s14
	v_mov_b32_e32 v71, s12
	v_mov_b32_e32 v72, s13
	v_mov_b32_e32 v73, s11
	v_pk_add_f32 v[70:71], s[8:9], v[70:71]
	v_pk_add_f32 v[72:73], s[0:1], v[72:73]
	s_mov_b32 s0, 0x3a800000
	v_pk_add_f32 v[70:71], v[70:71], v[72:73]
	s_nop 0
	v_pk_mul_f32 v[70:71], v[70:71], s[0:1] op_sel_hi:[1,0]
	s_nop 0
	v_fma_f32 v59, -v71, v71, v70
	v_max_f32_e32 v59, 0, v59
	v_add_f32_e32 v59, 0x358637bd, v59
	v_mul_f32_e32 v67, 0x4b800000, v59
	v_cmp_gt_f32_e64 s[0:1], s40, v59
	s_nop 1
	v_cndmask_b32_e64 v59, v59, v67, s[0:1]
	v_rsq_f32_e32 v59, v59
	s_nop 0
	v_mul_f32_e32 v67, 0x45800000, v59
	v_cndmask_b32_e64 v59, v59, v67, s[0:1]
	ds_write2st64_b32 v16, v71, v59 offset1:2
